# xn_phase rows remapped block-contiguous (block takes 68 consecutive rows, waves interleaved), loads of a row issued up front, ln gamma/beta hoisted
# baseline (speedup 1.0000x reference)
; DI int ltid() { int t = threadIdx.x; asm volatile("" : "+v"(t)); return t; }
; DI unsigned pack2(float a, float b) { f2 v = {a, b}; bf2 c = __builtin_convertvector(v, bf2); return __builtin_bit_cast(unsigned, c); }
; DI void xn_phase(const Params& p, const float* stats, const float* g, const float* bta, int l, int sc_off, int sh_off) {
;   const int tid = ltid(), wave = tid >> 6, lane = tid & 63;
;   for (int row = blockIdx.x * 4 + wave; row < NTOK; row += gridDim.x * 4) {
;     const int b = row / TPB, s = row % TPB;
;     const int mi = s < CTXL ? 8 : b;
;     const float* mv = p.modv + ((size_t)l * 9 + mi) * 6144;
;     const f32x4* xr = (const f32x4*)(stats ? p.X + (size_t)row * 1024 : in_row(p, row));
;     const f32x4 xv0 = xr[lane], xv1 = xr[lane + 64], xv2 = xr[lane + 128], xv3 = xr[lane + 192];
;     float mean = 0.f, rstd = 1.f;
;     if (stats) row_stats(stats, row, mean, rstd);
;     uint2* dst = (uint2*)(p.XN + (size_t)row * 1024);
; #pragma unroll
;     for (int j = 0; j < 4; ++j) {
;       const int c4 = lane + 64 * j;
;       const f32x4 vq = j == 0 ? xv0 : (j == 1 ? xv1 : (j == 2 ? xv2 : xv3));
;       float4 v = make_float4(vq.x, vq.y, vq.z, vq.w);
;       if (stats) {
;         float4 gv = ((const float4*)g)[c4], bv = ((const float4*)bta)[c4];
;         v.x = (v.x - mean) * rstd * gv.x + bv.x; v.y = (v.y - mean) * rstd * gv.y + bv.y;
;         v.z = (v.z - mean) * rstd * gv.z + bv.z; v.w = (v.w - mean) * rstd * gv.w + bv.w;
;       }
;       float4 sc = ((const float4*)(mv + sc_off))[c4], sh = ((const float4*)(mv + sh_off))[c4];
;       uint2 o;
;       o.x = pack2(v.x * (1.f + sc.x) + sh.x, v.y * (1.f + sc.y) + sh.y);
;       o.y = pack2(v.z * (1.f + sc.z) + sh.z, v.w * (1.f + sc.w) + sh.w);
;       dst[c4] = o;
;     }
;   }
.LxnF1_pre:
	v_readlane_b32 s12, v254, 59
	v_readlane_b32 s13, v254, 60
	global_load_dwordx4 v[88:91], v[20:21], off
	global_load_dwordx4 v[92:95], v[20:21], off offset:1024
	global_load_dwordx4 v[96:99], v[20:21], off offset:2048
	global_load_dwordx4 v[100:103], v[20:21], off offset:3072
	global_load_dwordx4 v[104:107], v[22:23], off
	global_load_dwordx4 v[108:111], v[22:23], off offset:1024
	global_load_dwordx4 v[112:115], v[22:23], off offset:2048
	global_load_dwordx4 v[116:119], v[22:23], off offset:3072
	v_and_b32_e32 v0, 3, v16
	v_lshrrev_b32_e32 v16, 2, v16
	v_mul_u32_u24_e32 v16, 0x44, v16
	v_add_u32_e32 v16, v16, v0
	s_mov_b32 s6, 17
	v_lshlrev_b32_e32 v38, 4, v18
	v_mov_b32_e32 v39, v144
.LxnF1_loop:
	s_mov_b32 s4, 0x78787879
	v_mul_hi_i32 v0, v16, s4
	v_lshrrev_b32_e32 v1, 31, v0
	v_ashrrev_i32_e32 v0, 11, v0
	v_add_u32_e32 v34, v0, v1
	v_mul_i32_i24_e32 v0, 0x1100, v34
	v_sub_u32_e32 v4, v16, v0
	v_cmp_gt_i32_e64 s[8:9], s33, v4
	v_ashrrev_i32_e32 v17, 31, v16
	v_mov_b64_e32 v[2:3], s[58:59]
	v_mov_b64_e32 v[0:1], v[16:17]
	v_lshlrev_b64 v[0:1], 12, v[0:1]
	v_lshl_add_u64 v[0:1], v[2:3], 0, v[0:1]
	v_lshl_add_u64 v[0:1], v[0:1], 0, v[38:39]
	v_lshlrev_b64 v[32:33], 6, v[16:17]
	v_lshl_add_u64 v[32:33], s[12:13], 0, v[32:33]
	global_load_dwordx4 v[56:59], v[32:33], off
	global_load_dwordx4 v[60:63], v[32:33], off offset:16
	global_load_dwordx4 v[64:67], v[32:33], off offset:32
	global_load_dwordx4 v[68:71], v[32:33], off offset:48
	global_load_dwordx4 v[72:75], v[0:1], off
	global_load_dwordx4 v[76:79], v[0:1], off offset:1024
	global_load_dwordx4 v[80:83], v[0:1], off offset:2048
	global_load_dwordx4 v[84:87], v[0:1], off offset:3072
	v_cndmask_b32_e64 v34, v34, 8, s[8:9]
	v_readlane_b32 s4, v255, 46
	v_ashrrev_i32_e32 v35, 31, v34
	v_readlane_b32 s5, v255, 47
	v_mov_b64_e32 v[36:37], s[68:69]
	s_movk_i32 s8, 0x6000
	v_lshl_add_u64 v[34:35], s[4:5], 0, v[34:35]
	v_mad_u64_u32 v[44:45], s[4:5], v34, s8, v[36:37]
	v_mov_b32_e32 v34, v45
	v_mad_u64_u32 v[34:35], s[4:5], v35, s8, v[34:35]
	v_mov_b32_e32 v45, v34
	s_mov_b64 s[4:5], 0x4000
	v_lshl_add_u64 v[36:37], v[44:45], 0, s[4:5]
	s_mov_b64 s[4:5], 0x3000
	v_lshl_add_u64 v[44:45], v[44:45], 0, s[4:5]
	v_lshl_add_u64 v[40:41], v[36:37], 0, v[38:39]
	v_lshl_add_u64 v[42:43], v[44:45], 0, v[38:39]
	global_load_dwordx4 v[120:123], v[40:41], off
	global_load_dwordx4 v[124:127], v[40:41], off offset:1024
	global_load_dwordx4 v[128:131], v[40:41], off offset:2048
	global_load_dwordx4 v[132:135], v[40:41], off offset:3072
	global_load_dwordx4 v[146:149], v[42:43], off
	global_load_dwordx4 v[150:153], v[42:43], off offset:1024
	global_load_dwordx4 v[154:157], v[42:43], off offset:2048
	global_load_dwordx4 v[158:161], v[42:43], off offset:3072
	v_lshlrev_b64 v[34:35], 11, v[16:17]
	v_lshl_add_u64 v[34:35], v[24:25], 0, v[34:35]
	s_waitcnt vmcnt(12)
	v_add_f32_e32 v2, v56, v58
	v_add_f32_e32 v3, v57, v59
	v_add_f32_e32 v4, v60, v62
	v_add_f32_e32 v5, v61, v63
	v_add_f32_e32 v2, v2, v4
	v_add_f32_e32 v3, v3, v5
	v_add_f32_e32 v4, v64, v66
	v_add_f32_e32 v5, v65, v67
	v_add_f32_e32 v2, v2, v4
	v_add_f32_e32 v3, v3, v5
	v_add_f32_e32 v4, v68, v70
	v_add_f32_e32 v5, v69, v71
	v_add_f32_e32 v2, v2, v4
	v_add_f32_e32 v3, v3, v5
	v_mul_f32_e32 v36, 0x3a800000, v2
	v_mul_f32_e32 v3, 0x3a800000, v3
	v_fma_f32 v19, -v36, v36, v3
	v_max_f32_e32 v19, 0, v19
	v_add_f32_e32 v19, 0x3727c5ac, v19
	v_mul_f32_e32 v27, 0x4b800000, v19
	s_mov_b32 s4, 0x800000
	v_cmp_gt_f32_e32 vcc, s4, v19
	s_nop 1
	v_cndmask_b32_e32 v19, v19, v27, vcc
	v_rsq_f32_e32 v19, v19
	s_nop 0
	v_mul_f32_e32 v27, 0x45800000, v19
	v_cndmask_b32_e32 v32, v19, v27, vcc
	s_waitcnt vmcnt(0)
	v_pk_add_f32 v[72:73], v[72:73], v[36:37] op_sel_hi:[1,0] neg_lo:[0,1] neg_hi:[0,1]
	v_pk_add_f32 v[74:75], v[74:75], v[36:37] op_sel_hi:[1,0] neg_lo:[0,1] neg_hi:[0,1]
	v_pk_add_f32 v[76:77], v[76:77], v[36:37] op_sel_hi:[1,0] neg_lo:[0,1] neg_hi:[0,1]
	v_pk_add_f32 v[78:79], v[78:79], v[36:37] op_sel_hi:[1,0] neg_lo:[0,1] neg_hi:[0,1]
	v_pk_add_f32 v[80:81], v[80:81], v[36:37] op_sel_hi:[1,0] neg_lo:[0,1] neg_hi:[0,1]
	v_pk_add_f32 v[82:83], v[82:83], v[36:37] op_sel_hi:[1,0] neg_lo:[0,1] neg_hi:[0,1]
	v_pk_add_f32 v[84:85], v[84:85], v[36:37] op_sel_hi:[1,0] neg_lo:[0,1] neg_hi:[0,1]
	v_pk_add_f32 v[86:87], v[86:87], v[36:37] op_sel_hi:[1,0] neg_lo:[0,1] neg_hi:[0,1]
	v_pk_add_f32 v[120:121], v[120:121], 1.0 op_sel_hi:[1,0]
	v_pk_add_f32 v[122:123], v[122:123], 1.0 op_sel_hi:[1,0]
	v_pk_add_f32 v[124:125], v[124:125], 1.0 op_sel_hi:[1,0]
	v_pk_add_f32 v[126:127], v[126:127], 1.0 op_sel_hi:[1,0]
	v_pk_add_f32 v[128:129], v[128:129], 1.0 op_sel_hi:[1,0]
	v_pk_add_f32 v[130:131], v[130:131], 1.0 op_sel_hi:[1,0]
	v_pk_add_f32 v[132:133], v[132:133], 1.0 op_sel_hi:[1,0]
	v_pk_add_f32 v[134:135], v[134:135], 1.0 op_sel_hi:[1,0]
	v_pk_mul_f32 v[72:73], v[32:33], v[72:73] op_sel_hi:[0,1]
	v_pk_mul_f32 v[74:75], v[32:33], v[74:75] op_sel_hi:[0,1]
	v_pk_mul_f32 v[76:77], v[32:33], v[76:77] op_sel_hi:[0,1]
	v_pk_mul_f32 v[78:79], v[32:33], v[78:79] op_sel_hi:[0,1]
	v_pk_mul_f32 v[80:81], v[32:33], v[80:81] op_sel_hi:[0,1]
	v_pk_mul_f32 v[82:83], v[32:33], v[82:83] op_sel_hi:[0,1]
	v_pk_mul_f32 v[84:85], v[32:33], v[84:85] op_sel_hi:[0,1]
	v_pk_mul_f32 v[86:87], v[32:33], v[86:87] op_sel_hi:[0,1]
	v_pk_fma_f32 v[72:73], v[72:73], v[88:89], v[104:105]
	v_pk_fma_f32 v[74:75], v[74:75], v[90:91], v[106:107]
	v_pk_fma_f32 v[76:77], v[76:77], v[92:93], v[108:109]
	v_pk_fma_f32 v[78:79], v[78:79], v[94:95], v[110:111]
	v_pk_fma_f32 v[80:81], v[80:81], v[96:97], v[112:113]
	v_pk_fma_f32 v[82:83], v[82:83], v[98:99], v[114:115]
	v_pk_fma_f32 v[84:85], v[84:85], v[100:101], v[116:117]
	v_pk_fma_f32 v[86:87], v[86:87], v[102:103], v[118:119]
	v_pk_fma_f32 v[72:73], v[72:73], v[120:121], v[146:147]
	v_pk_fma_f32 v[74:75], v[74:75], v[122:123], v[148:149]
	v_pk_fma_f32 v[76:77], v[76:77], v[124:125], v[150:151]
	v_pk_fma_f32 v[78:79], v[78:79], v[126:127], v[152:153]
	v_pk_fma_f32 v[80:81], v[80:81], v[128:129], v[154:155]
	v_pk_fma_f32 v[82:83], v[82:83], v[130:131], v[156:157]
	v_pk_fma_f32 v[84:85], v[84:85], v[132:133], v[158:159]
	v_pk_fma_f32 v[86:87], v[86:87], v[134:135], v[160:161]
	v_cvt_pk_bf16_f32 v72, v72, v73
	v_cvt_pk_bf16_f32 v73, v74, v75
	v_cvt_pk_bf16_f32 v76, v76, v77
	v_cvt_pk_bf16_f32 v77, v78, v79
	v_cvt_pk_bf16_f32 v80, v80, v81
	v_cvt_pk_bf16_f32 v81, v82, v83
	v_cvt_pk_bf16_f32 v84, v84, v85
	v_cvt_pk_bf16_f32 v85, v86, v87
	global_store_dwordx2 v[34:35], v[72:73], off
	global_store_dwordx2 v[34:35], v[76:77], off offset:512
	global_store_dwordx2 v[34:35], v[80:81], off offset:1024
	global_store_dwordx2 v[34:35], v[84:85], off offset:1536
	v_add_u32_e32 v16, 4, v16
	s_sub_i32 s6, s6, 1
	s_cmp_lg_u32 s6, 0
	s_cbranch_scc1 .LxnF1_loop
	s_branch .LBB0_69

; DI int ltid() { int t = threadIdx.x; asm volatile("" : "+v"(t)); return t; }
; DI unsigned pack2(float a, float b) { f2 v = {a, b}; bf2 c = __builtin_convertvector(v, bf2); return __builtin_bit_cast(unsigned, c); }
; DI void xn_phase(const Params& p, const float* stats, const float* g, const float* bta, int l, int sc_off, int sh_off) {
;   const int tid = ltid(), wave = tid >> 6, lane = tid & 63;
;   for (int row = blockIdx.x * 4 + wave; row < NTOK; row += gridDim.x * 4) {
;     const int b = row / TPB, s = row % TPB;
;     const int mi = s < CTXL ? 8 : b;
;     const float* mv = p.modv + ((size_t)l * 9 + mi) * 6144;
;     const f32x4* xr = (const f32x4*)(stats ? p.X + (size_t)row * 1024 : in_row(p, row));
;     const f32x4 xv0 = xr[lane], xv1 = xr[lane + 64], xv2 = xr[lane + 128], xv3 = xr[lane + 192];
;     float mean = 0.f, rstd = 1.f;
;     if (stats) row_stats(stats, row, mean, rstd);
;     uint2* dst = (uint2*)(p.XN + (size_t)row * 1024);
; #pragma unroll
;     for (int j = 0; j < 4; ++j) {
;       const int c4 = lane + 64 * j;
;       const f32x4 vq = j == 0 ? xv0 : (j == 1 ? xv1 : (j == 2 ? xv2 : xv3));
;       float4 v = make_float4(vq.x, vq.y, vq.z, vq.w);
;       if (stats) {
;         float4 gv = ((const float4*)g)[c4], bv = ((const float4*)bta)[c4];
;         v.x = (v.x - mean) * rstd * gv.x + bv.x; v.y = (v.y - mean) * rstd * gv.y + bv.y;
;         v.z = (v.z - mean) * rstd * gv.z + bv.z; v.w = (v.w - mean) * rstd * gv.w + bv.w;
;       }
;       float4 sc = ((const float4*)(mv + sc_off))[c4], sh = ((const float4*)(mv + sh_off))[c4];
;       uint2 o;
;       o.x = pack2(v.x * (1.f + sc.x) + sh.x, v.y * (1.f + sc.y) + sh.y);
;       o.y = pack2(v.z * (1.f + sc.z) + sh.z, v.w * (1.f + sc.w) + sh.w);
;       dst[c4] = o;
;     }
;   }
.LxnF2_pre:
	global_load_dwordx4 v[88:91], v[20:21], off
	global_load_dwordx4 v[92:95], v[20:21], off offset:1024
	global_load_dwordx4 v[96:99], v[20:21], off offset:2048
	global_load_dwordx4 v[100:103], v[20:21], off offset:3072
	global_load_dwordx4 v[104:107], v[22:23], off
	global_load_dwordx4 v[108:111], v[22:23], off offset:1024
	global_load_dwordx4 v[112:115], v[22:23], off offset:2048
	global_load_dwordx4 v[116:119], v[22:23], off offset:3072
	v_and_b32_e32 v0, 3, v16
	v_lshrrev_b32_e32 v16, 2, v16
	v_mul_u32_u24_e32 v16, 0x44, v16
	v_add_u32_e32 v16, v16, v0
	s_mov_b32 s6, 17
	v_lshlrev_b32_e32 v38, 4, v18
	v_mov_b32_e32 v39, v144
.LxnF2_loop:
	s_mov_b32 s4, 0x78787879
	v_mul_hi_i32 v0, v16, s4
	v_lshrrev_b32_e32 v1, 31, v0
	v_ashrrev_i32_e32 v0, 11, v0
	v_add_u32_e32 v34, v0, v1
	v_mul_i32_i24_e32 v0, 0x1100, v34
	v_sub_u32_e32 v4, v16, v0
	v_cmp_gt_i32_e64 s[8:9], s33, v4
	v_ashrrev_i32_e32 v17, 31, v16
	v_mov_b64_e32 v[2:3], s[58:59]
	v_mov_b64_e32 v[0:1], v[16:17]
	v_lshlrev_b64 v[0:1], 12, v[0:1]
	v_lshl_add_u64 v[0:1], v[2:3], 0, v[0:1]
	v_lshl_add_u64 v[0:1], v[0:1], 0, v[38:39]
	v_lshlrev_b64 v[32:33], 6, v[16:17]
	v_lshl_add_u64 v[32:33], s[10:11], 0, v[32:33]
	global_load_dwordx4 v[56:59], v[32:33], off
	global_load_dwordx4 v[60:63], v[32:33], off offset:16
	global_load_dwordx4 v[64:67], v[32:33], off offset:32
	global_load_dwordx4 v[68:71], v[32:33], off offset:48
	global_load_dwordx4 v[72:75], v[0:1], off
	global_load_dwordx4 v[76:79], v[0:1], off offset:1024
	global_load_dwordx4 v[80:83], v[0:1], off offset:2048
	global_load_dwordx4 v[84:87], v[0:1], off offset:3072
	v_cndmask_b32_e64 v34, v34, 8, s[8:9]
	v_readlane_b32 s4, v255, 46
	v_ashrrev_i32_e32 v35, 31, v34
	v_readlane_b32 s5, v255, 47
	v_mov_b64_e32 v[36:37], s[68:69]
	s_movk_i32 s8, 0x6000
	v_lshl_add_u64 v[34:35], s[4:5], 0, v[34:35]
	v_mad_u64_u32 v[44:45], s[4:5], v34, s8, v[36:37]
	v_mov_b32_e32 v34, v45
	v_mad_u64_u32 v[34:35], s[4:5], v35, s8, v[34:35]
	v_mov_b32_e32 v45, v34
	v_lshl_add_u64 v[36:37], v[44:45], 0, s[28:29]
	v_lshl_add_u64 v[40:41], v[36:37], 0, v[38:39]
	v_lshl_add_u64 v[42:43], v[44:45], 0, v[38:39]
	global_load_dwordx4 v[120:123], v[40:41], off
	global_load_dwordx4 v[124:127], v[40:41], off offset:1024
	global_load_dwordx4 v[128:131], v[40:41], off offset:2048
	global_load_dwordx4 v[132:135], v[40:41], off offset:3072
	global_load_dwordx4 v[146:149], v[42:43], off
	global_load_dwordx4 v[150:153], v[42:43], off offset:1024
	global_load_dwordx4 v[154:157], v[42:43], off offset:2048
	global_load_dwordx4 v[158:161], v[42:43], off offset:3072
	v_lshlrev_b64 v[34:35], 11, v[16:17]
	v_lshl_add_u64 v[34:35], v[24:25], 0, v[34:35]
	s_waitcnt vmcnt(12)
	v_add_f32_e32 v2, v56, v58
	v_add_f32_e32 v3, v57, v59
	v_add_f32_e32 v4, v60, v62
	v_add_f32_e32 v5, v61, v63
	v_add_f32_e32 v2, v2, v4
	v_add_f32_e32 v3, v3, v5
	v_add_f32_e32 v4, v64, v66
	v_add_f32_e32 v5, v65, v67
	v_add_f32_e32 v2, v2, v4
	v_add_f32_e32 v3, v3, v5
	v_add_f32_e32 v4, v68, v70
	v_add_f32_e32 v5, v69, v71
	v_add_f32_e32 v2, v2, v4
	v_add_f32_e32 v3, v3, v5
	v_mul_f32_e32 v36, 0x3a800000, v2
	v_mul_f32_e32 v3, 0x3a800000, v3
	v_fma_f32 v19, -v36, v36, v3
	v_max_f32_e32 v19, 0, v19
	v_add_f32_e32 v19, 0x3727c5ac, v19
	v_mul_f32_e32 v27, 0x4b800000, v19
	s_mov_b32 s4, 0x800000
	v_cmp_gt_f32_e32 vcc, s4, v19
	s_nop 1
	v_cndmask_b32_e32 v19, v19, v27, vcc
	v_rsq_f32_e32 v19, v19
	s_nop 0
	v_mul_f32_e32 v27, 0x45800000, v19
	v_cndmask_b32_e32 v32, v19, v27, vcc
	s_waitcnt vmcnt(0)
	v_pk_add_f32 v[72:73], v[72:73], v[36:37] op_sel_hi:[1,0] neg_lo:[0,1] neg_hi:[0,1]
	v_pk_add_f32 v[74:75], v[74:75], v[36:37] op_sel_hi:[1,0] neg_lo:[0,1] neg_hi:[0,1]
	v_pk_add_f32 v[76:77], v[76:77], v[36:37] op_sel_hi:[1,0] neg_lo:[0,1] neg_hi:[0,1]
	v_pk_add_f32 v[78:79], v[78:79], v[36:37] op_sel_hi:[1,0] neg_lo:[0,1] neg_hi:[0,1]
	v_pk_add_f32 v[80:81], v[80:81], v[36:37] op_sel_hi:[1,0] neg_lo:[0,1] neg_hi:[0,1]
	v_pk_add_f32 v[82:83], v[82:83], v[36:37] op_sel_hi:[1,0] neg_lo:[0,1] neg_hi:[0,1]
	v_pk_add_f32 v[84:85], v[84:85], v[36:37] op_sel_hi:[1,0] neg_lo:[0,1] neg_hi:[0,1]
	v_pk_add_f32 v[86:87], v[86:87], v[36:37] op_sel_hi:[1,0] neg_lo:[0,1] neg_hi:[0,1]
	v_pk_add_f32 v[120:121], v[120:121], 1.0 op_sel_hi:[1,0]
	v_pk_add_f32 v[122:123], v[122:123], 1.0 op_sel_hi:[1,0]
	v_pk_add_f32 v[124:125], v[124:125], 1.0 op_sel_hi:[1,0]
	v_pk_add_f32 v[126:127], v[126:127], 1.0 op_sel_hi:[1,0]
	v_pk_add_f32 v[128:129], v[128:129], 1.0 op_sel_hi:[1,0]
	v_pk_add_f32 v[130:131], v[130:131], 1.0 op_sel_hi:[1,0]
	v_pk_add_f32 v[132:133], v[132:133], 1.0 op_sel_hi:[1,0]
	v_pk_add_f32 v[134:135], v[134:135], 1.0 op_sel_hi:[1,0]
	v_pk_mul_f32 v[72:73], v[32:33], v[72:73] op_sel_hi:[0,1]
	v_pk_mul_f32 v[74:75], v[32:33], v[74:75] op_sel_hi:[0,1]
	v_pk_mul_f32 v[76:77], v[32:33], v[76:77] op_sel_hi:[0,1]
	v_pk_mul_f32 v[78:79], v[32:33], v[78:79] op_sel_hi:[0,1]
	v_pk_mul_f32 v[80:81], v[32:33], v[80:81] op_sel_hi:[0,1]
	v_pk_mul_f32 v[82:83], v[32:33], v[82:83] op_sel_hi:[0,1]
	v_pk_mul_f32 v[84:85], v[32:33], v[84:85] op_sel_hi:[0,1]
	v_pk_mul_f32 v[86:87], v[32:33], v[86:87] op_sel_hi:[0,1]
	v_pk_fma_f32 v[72:73], v[72:73], v[88:89], v[104:105]
	v_pk_fma_f32 v[74:75], v[74:75], v[90:91], v[106:107]
	v_pk_fma_f32 v[76:77], v[76:77], v[92:93], v[108:109]
	v_pk_fma_f32 v[78:79], v[78:79], v[94:95], v[110:111]
	v_pk_fma_f32 v[80:81], v[80:81], v[96:97], v[112:113]
	v_pk_fma_f32 v[82:83], v[82:83], v[98:99], v[114:115]
	v_pk_fma_f32 v[84:85], v[84:85], v[100:101], v[116:117]
	v_pk_fma_f32 v[86:87], v[86:87], v[102:103], v[118:119]
	v_pk_fma_f32 v[72:73], v[72:73], v[120:121], v[146:147]
	v_pk_fma_f32 v[74:75], v[74:75], v[122:123], v[148:149]
	v_pk_fma_f32 v[76:77], v[76:77], v[124:125], v[150:151]
	v_pk_fma_f32 v[78:79], v[78:79], v[126:127], v[152:153]
	v_pk_fma_f32 v[80:81], v[80:81], v[128:129], v[154:155]
	v_pk_fma_f32 v[82:83], v[82:83], v[130:131], v[156:157]
	v_pk_fma_f32 v[84:85], v[84:85], v[132:133], v[158:159]
	v_pk_fma_f32 v[86:87], v[86:87], v[134:135], v[160:161]
	v_cvt_pk_bf16_f32 v72, v72, v73
	v_cvt_pk_bf16_f32 v73, v74, v75
	v_cvt_pk_bf16_f32 v76, v76, v77
	v_cvt_pk_bf16_f32 v77, v78, v79
	v_cvt_pk_bf16_f32 v80, v80, v81
	v_cvt_pk_bf16_f32 v81, v82, v83
	v_cvt_pk_bf16_f32 v84, v84, v85
	v_cvt_pk_bf16_f32 v85, v86, v87
	global_store_dwordx2 v[34:35], v[72:73], off
	global_store_dwordx2 v[34:35], v[76:77], off offset:512
	global_store_dwordx2 v[34:35], v[80:81], off offset:1024
	global_store_dwordx2 v[34:35], v[84:85], off offset:1536
	v_add_u32_e32 v16, 4, v16
	s_sub_i32 s6, s6, 1
	s_cmp_lg_u32 s6, 0
	s_cbranch_scc1 .LxnF2_loop
	s_branch .LBB0_978
